# fused norms: residual stores and gain loads issued before the in-epilogue barrier spin
# speedup vs baseline: 1.0050x; 1.0050x over previous
; __device__ __forceinline__ void rmsnorm_rows_f32(float* x, const float* gain, int nrows, int gw, int ngw, int lane) {
;     f32x4 gv[4];
; #pragma unroll
;     for (int j = 0; j < 4; ++j) gv[j] = *((const f32x4*)gain + lane + 64 * j);
.Lfn_na:
	v_mov_b32_e32 v0, 0x25940
	ds_read_b64 v[140:141], v0
	v_lshlrev_b32_e32 v0, 2, v203
	s_waitcnt lgkmcnt(0)
	v_readfirstlane_b32 s100, v140
	v_readfirstlane_b32 s101, v141
	s_nop 4
	global_load_dwordx4 v[144:147], v0, s[100:101]
	global_load_dwordx4 v[148:151], v0, s[100:101] offset:16
	global_load_dwordx4 v[152:155], v0, s[100:101] offset:512
	global_load_dwordx4 v[156:159], v0, s[100:101] offset:528
	v_readfirstlane_b32 s100, v192
	s_cmp_lg_u32 s100, 0
	s_cbranch_scc1 .Lfn_bw
	s_mov_b32 s101, 0

; __device__ __forceinline__ void rmsnorm_rows_f32(float* x, const float* gain, int nrows, int gw, int ngw, int lane) {
;     ...
;         f32x4* xr = (f32x4*)(x + (size_t)r * D) + lane; f32x4 v[4]; float s = 0.f;
; #pragma unroll
;         for (int j = 0; j < 4; ++j) { v[j] = xr[64 * j]; s += (v[j].x * v[j].x + v[j].y * v[j].y) + (v[j].z * v[j].z + v[j].w * v[j].w); }
;         const float rs = rsqrtf(wave_sum(s) * (1.f / D) + 1e-6f);
; #pragma unroll
;         for (int j = 0; j < 4; ++j) xr[64 * j] = v[j] * rs * gv[j];
.Lfn_bw:
	s_barrier
	v_lshlrev_b32_e32 v136, 2, v202
	v_add_u32_e32 v137, 0x10000, v136
	v_add_u32_e32 v138, 0x20000, v136
	v_add_u32_e32 v139, 0x30000, v136
	global_load_dword v210, v136, s[98:99] sc1
	global_load_dword v211, v137, s[98:99] sc1
	global_load_dword v212, v138, s[98:99] sc1
	global_load_dword v213, v139, s[98:99] sc1
	global_load_dword v214, v136, s[98:99] offset:64 sc1
	global_load_dword v215, v137, s[98:99] offset:64 sc1
	global_load_dword v216, v138, s[98:99] offset:64 sc1
	global_load_dword v217, v139, s[98:99] offset:64 sc1
	global_load_dword v218, v136, s[98:99] offset:128 sc1
	global_load_dword v219, v137, s[98:99] offset:128 sc1
	global_load_dword v220, v138, s[98:99] offset:128 sc1
	global_load_dword v221, v139, s[98:99] offset:128 sc1
	global_load_dword v222, v136, s[98:99] offset:192 sc1
	global_load_dword v223, v137, s[98:99] offset:192 sc1
	global_load_dword v224, v138, s[98:99] offset:192 sc1
	global_load_dword v225, v139, s[98:99] offset:192 sc1
	global_load_dword v226, v136, s[98:99] offset:512 sc1
	global_load_dword v227, v137, s[98:99] offset:512 sc1
	global_load_dword v228, v138, s[98:99] offset:512 sc1
	global_load_dword v229, v139, s[98:99] offset:512 sc1
	global_load_dword v230, v136, s[98:99] offset:576 sc1
	global_load_dword v231, v137, s[98:99] offset:576 sc1
	global_load_dword v232, v138, s[98:99] offset:576 sc1
	global_load_dword v233, v139, s[98:99] offset:576 sc1
	global_load_dword v234, v136, s[98:99] offset:640 sc1
	global_load_dword v235, v137, s[98:99] offset:640 sc1
	global_load_dword v236, v138, s[98:99] offset:640 sc1
	global_load_dword v237, v139, s[98:99] offset:640 sc1
	global_load_dword v238, v136, s[98:99] offset:704 sc1
	global_load_dword v239, v137, s[98:99] offset:704 sc1
	global_load_dword v240, v138, s[98:99] offset:704 sc1
	global_load_dword v241, v139, s[98:99] offset:704 sc1
	v_mov_b32_e32 v142, 0x358637bd
	s_waitcnt vmcnt(0)
	v_add_f32_e32 v210, v210, v211
	v_add_f32_e32 v210, v210, v212
	v_add_f32_e32 v210, v210, v213
	v_fmamk_f32 v210, v210, 0x3a800000, v142
	v_add_f32_e32 v214, v214, v215
	v_add_f32_e32 v214, v214, v216
	v_add_f32_e32 v214, v214, v217
	v_fmamk_f32 v214, v214, 0x3a800000, v142
	v_add_f32_e32 v218, v218, v219
	v_add_f32_e32 v218, v218, v220
	v_add_f32_e32 v218, v218, v221
	v_fmamk_f32 v218, v218, 0x3a800000, v142
	v_add_f32_e32 v222, v222, v223
	v_add_f32_e32 v222, v222, v224
	v_add_f32_e32 v222, v222, v225
	v_fmamk_f32 v222, v222, 0x3a800000, v142
	v_add_f32_e32 v226, v226, v227
	v_add_f32_e32 v226, v226, v228
	v_add_f32_e32 v226, v226, v229
	v_fmamk_f32 v226, v226, 0x3a800000, v142
	v_add_f32_e32 v230, v230, v231
	v_add_f32_e32 v230, v230, v232
	v_add_f32_e32 v230, v230, v233
	v_fmamk_f32 v230, v230, 0x3a800000, v142
	v_add_f32_e32 v234, v234, v235
	v_add_f32_e32 v234, v234, v236
	v_add_f32_e32 v234, v234, v237
	v_fmamk_f32 v234, v234, 0x3a800000, v142
	v_add_f32_e32 v238, v238, v239
	v_add_f32_e32 v238, v238, v240
	v_add_f32_e32 v238, v238, v241
	v_fmamk_f32 v238, v238, 0x3a800000, v142
	v_rsq_f32_e32 v210, v210
	v_rsq_f32_e32 v214, v214
	v_rsq_f32_e32 v218, v218
	v_rsq_f32_e32 v222, v222
	v_rsq_f32_e32 v226, v226
	v_rsq_f32_e32 v230, v230
	v_rsq_f32_e32 v234, v234
	v_rsq_f32_e32 v238, v238
	s_nop 0
	v_pk_mul_f32 v[128:129], v[128:129], v[210:211] op_sel_hi:[1,0]
	v_pk_mul_f32 v[130:131], v[130:131], v[210:211] op_sel_hi:[1,0]
	v_pk_mul_f32 v[124:125], v[124:125], v[210:211] op_sel_hi:[1,0]
	v_pk_mul_f32 v[126:127], v[126:127], v[210:211] op_sel_hi:[1,0]
	v_pk_mul_f32 v[128:129], v[144:145], v[128:129]
	v_pk_mul_f32 v[130:131], v[146:147], v[130:131]
	v_pk_mul_f32 v[124:125], v[148:149], v[124:125]
	v_pk_mul_f32 v[126:127], v[150:151], v[126:127]
	global_store_dwordx4 v182, v[128:131], s[66:67]
	global_store_dwordx4 v182, v[124:127], s[66:67] offset:16
	v_pk_mul_f32 v[120:121], v[120:121], v[210:211] op_sel_hi:[1,0]
	v_pk_mul_f32 v[122:123], v[122:123], v[210:211] op_sel_hi:[1,0]
	v_pk_mul_f32 v[116:117], v[116:117], v[210:211] op_sel_hi:[1,0]
	v_pk_mul_f32 v[118:119], v[118:119], v[210:211] op_sel_hi:[1,0]
	v_pk_mul_f32 v[120:121], v[152:153], v[120:121]
	v_pk_mul_f32 v[122:123], v[154:155], v[122:123]
	v_pk_mul_f32 v[116:117], v[156:157], v[116:117]
	v_pk_mul_f32 v[118:119], v[158:159], v[118:119]
	global_store_dwordx4 v182, v[120:123], s[66:67] offset:512
	global_store_dwordx4 v182, v[116:119], s[66:67] offset:528
	v_pk_mul_f32 v[112:113], v[112:113], v[214:215] op_sel_hi:[1,0]
	v_pk_mul_f32 v[114:115], v[114:115], v[214:215] op_sel_hi:[1,0]
	v_pk_mul_f32 v[108:109], v[108:109], v[214:215] op_sel_hi:[1,0]
	v_pk_mul_f32 v[110:111], v[110:111], v[214:215] op_sel_hi:[1,0]
	v_pk_mul_f32 v[112:113], v[144:145], v[112:113]
	v_pk_mul_f32 v[114:115], v[146:147], v[114:115]
	v_pk_mul_f32 v[108:109], v[148:149], v[108:109]
	v_pk_mul_f32 v[110:111], v[150:151], v[110:111]
	global_store_dwordx4 v183, v[112:115], s[66:67]
	global_store_dwordx4 v183, v[108:111], s[66:67] offset:16
	v_pk_mul_f32 v[104:105], v[104:105], v[214:215] op_sel_hi:[1,0]
	v_pk_mul_f32 v[106:107], v[106:107], v[214:215] op_sel_hi:[1,0]
	v_pk_mul_f32 v[100:101], v[100:101], v[214:215] op_sel_hi:[1,0]
	v_pk_mul_f32 v[102:103], v[102:103], v[214:215] op_sel_hi:[1,0]
	v_pk_mul_f32 v[104:105], v[152:153], v[104:105]
	v_pk_mul_f32 v[106:107], v[154:155], v[106:107]
	v_pk_mul_f32 v[100:101], v[156:157], v[100:101]
	v_pk_mul_f32 v[102:103], v[158:159], v[102:103]
	global_store_dwordx4 v183, v[104:107], s[66:67] offset:512
	global_store_dwordx4 v183, v[100:103], s[66:67] offset:528
	v_pk_mul_f32 v[96:97], v[96:97], v[218:219] op_sel_hi:[1,0]
	v_pk_mul_f32 v[98:99], v[98:99], v[218:219] op_sel_hi:[1,0]
; __device__ __forceinline__ void rmsnorm_rows_f32(float* x, const float* gain, int nrows, int gw, int ngw, int lane) {
;     ...
; #pragma unroll
;         for (int j = 0; j < 4; ++j) xr[64 * j] = v[j] * rs * gv[j];
	v_pk_mul_f32 v[92:93], v[92:93], v[218:219] op_sel_hi:[1,0]
	v_pk_mul_f32 v[94:95], v[94:95], v[218:219] op_sel_hi:[1,0]
	v_pk_mul_f32 v[96:97], v[144:145], v[96:97]
	v_pk_mul_f32 v[98:99], v[146:147], v[98:99]
	v_pk_mul_f32 v[92:93], v[148:149], v[92:93]
	v_pk_mul_f32 v[94:95], v[150:151], v[94:95]
	global_store_dwordx4 v184, v[96:99], s[66:67]
	global_store_dwordx4 v184, v[92:95], s[66:67] offset:16
	v_pk_mul_f32 v[88:89], v[88:89], v[218:219] op_sel_hi:[1,0]
	v_pk_mul_f32 v[90:91], v[90:91], v[218:219] op_sel_hi:[1,0]
	v_pk_mul_f32 v[84:85], v[84:85], v[218:219] op_sel_hi:[1,0]
	v_pk_mul_f32 v[86:87], v[86:87], v[218:219] op_sel_hi:[1,0]
	v_pk_mul_f32 v[88:89], v[152:153], v[88:89]
	v_pk_mul_f32 v[90:91], v[154:155], v[90:91]
	v_pk_mul_f32 v[84:85], v[156:157], v[84:85]
	v_pk_mul_f32 v[86:87], v[158:159], v[86:87]
	global_store_dwordx4 v184, v[88:91], s[66:67] offset:512
	global_store_dwordx4 v184, v[84:87], s[66:67] offset:528
	v_pk_mul_f32 v[80:81], v[80:81], v[222:223] op_sel_hi:[1,0]
	v_pk_mul_f32 v[82:83], v[82:83], v[222:223] op_sel_hi:[1,0]
	v_pk_mul_f32 v[76:77], v[76:77], v[222:223] op_sel_hi:[1,0]
	v_pk_mul_f32 v[78:79], v[78:79], v[222:223] op_sel_hi:[1,0]
	v_pk_mul_f32 v[80:81], v[144:145], v[80:81]
	v_pk_mul_f32 v[82:83], v[146:147], v[82:83]
	v_pk_mul_f32 v[76:77], v[148:149], v[76:77]
	v_pk_mul_f32 v[78:79], v[150:151], v[78:79]
	global_store_dwordx4 v185, v[80:83], s[66:67]
	global_store_dwordx4 v185, v[76:79], s[66:67] offset:16
	v_pk_mul_f32 v[72:73], v[72:73], v[222:223] op_sel_hi:[1,0]
	v_pk_mul_f32 v[74:75], v[74:75], v[222:223] op_sel_hi:[1,0]
	v_pk_mul_f32 v[68:69], v[68:69], v[222:223] op_sel_hi:[1,0]
	v_pk_mul_f32 v[70:71], v[70:71], v[222:223] op_sel_hi:[1,0]
	v_pk_mul_f32 v[72:73], v[152:153], v[72:73]
	v_pk_mul_f32 v[74:75], v[154:155], v[74:75]
	v_pk_mul_f32 v[68:69], v[156:157], v[68:69]
	v_pk_mul_f32 v[70:71], v[158:159], v[70:71]
	global_store_dwordx4 v185, v[72:75], s[66:67] offset:512
	global_store_dwordx4 v185, v[68:71], s[66:67] offset:528
	v_pk_mul_f32 v[64:65], v[64:65], v[226:227] op_sel_hi:[1,0]
	v_pk_mul_f32 v[66:67], v[66:67], v[226:227] op_sel_hi:[1,0]
	v_pk_mul_f32 v[60:61], v[60:61], v[226:227] op_sel_hi:[1,0]
	v_pk_mul_f32 v[62:63], v[62:63], v[226:227] op_sel_hi:[1,0]
	v_pk_mul_f32 v[64:65], v[144:145], v[64:65]
	v_pk_mul_f32 v[66:67], v[146:147], v[66:67]
	v_pk_mul_f32 v[60:61], v[148:149], v[60:61]
	v_pk_mul_f32 v[62:63], v[150:151], v[62:63]
	global_store_dwordx4 v190, v[64:67], s[66:67]
	global_store_dwordx4 v190, v[60:63], s[66:67] offset:16
	v_pk_mul_f32 v[56:57], v[56:57], v[226:227] op_sel_hi:[1,0]
	v_pk_mul_f32 v[58:59], v[58:59], v[226:227] op_sel_hi:[1,0]
	v_pk_mul_f32 v[52:53], v[52:53], v[226:227] op_sel_hi:[1,0]
	v_pk_mul_f32 v[54:55], v[54:55], v[226:227] op_sel_hi:[1,0]
	v_pk_mul_f32 v[56:57], v[152:153], v[56:57]
	v_pk_mul_f32 v[58:59], v[154:155], v[58:59]
	v_pk_mul_f32 v[52:53], v[156:157], v[52:53]
	v_pk_mul_f32 v[54:55], v[158:159], v[54:55]
	global_store_dwordx4 v190, v[56:59], s[66:67] offset:512
	global_store_dwordx4 v190, v[52:55], s[66:67] offset:528
	v_pk_mul_f32 v[48:49], v[48:49], v[230:231] op_sel_hi:[1,0]
	v_pk_mul_f32 v[50:51], v[50:51], v[230:231] op_sel_hi:[1,0]
	v_pk_mul_f32 v[44:45], v[44:45], v[230:231] op_sel_hi:[1,0]
	v_pk_mul_f32 v[46:47], v[46:47], v[230:231] op_sel_hi:[1,0]
	v_pk_mul_f32 v[48:49], v[144:145], v[48:49]
	v_pk_mul_f32 v[50:51], v[146:147], v[50:51]
	v_pk_mul_f32 v[44:45], v[148:149], v[44:45]
	v_pk_mul_f32 v[46:47], v[150:151], v[46:47]
	global_store_dwordx4 v191, v[48:51], s[66:67]
	global_store_dwordx4 v191, v[44:47], s[66:67] offset:16
	v_pk_mul_f32 v[40:41], v[40:41], v[230:231] op_sel_hi:[1,0]
	v_pk_mul_f32 v[42:43], v[42:43], v[230:231] op_sel_hi:[1,0]
	v_pk_mul_f32 v[36:37], v[36:37], v[230:231] op_sel_hi:[1,0]
	v_pk_mul_f32 v[38:39], v[38:39], v[230:231] op_sel_hi:[1,0]
	v_pk_mul_f32 v[40:41], v[152:153], v[40:41]
	v_pk_mul_f32 v[42:43], v[154:155], v[42:43]
	v_pk_mul_f32 v[36:37], v[156:157], v[36:37]
	v_pk_mul_f32 v[38:39], v[158:159], v[38:39]
	global_store_dwordx4 v191, v[40:43], s[66:67] offset:512
	global_store_dwordx4 v191, v[36:39], s[66:67] offset:528
	v_pk_mul_f32 v[32:33], v[32:33], v[234:235] op_sel_hi:[1,0]
	v_pk_mul_f32 v[34:35], v[34:35], v[234:235] op_sel_hi:[1,0]
	v_pk_mul_f32 v[28:29], v[28:29], v[234:235] op_sel_hi:[1,0]
	v_pk_mul_f32 v[30:31], v[30:31], v[234:235] op_sel_hi:[1,0]
	v_pk_mul_f32 v[32:33], v[144:145], v[32:33]
	v_pk_mul_f32 v[34:35], v[146:147], v[34:35]
	v_pk_mul_f32 v[28:29], v[148:149], v[28:29]
	v_pk_mul_f32 v[30:31], v[150:151], v[30:31]
	global_store_dwordx4 v200, v[32:35], s[66:67]
	global_store_dwordx4 v200, v[28:31], s[66:67] offset:16
	v_pk_mul_f32 v[24:25], v[24:25], v[234:235] op_sel_hi:[1,0]
	v_pk_mul_f32 v[26:27], v[26:27], v[234:235] op_sel_hi:[1,0]
	v_pk_mul_f32 v[20:21], v[20:21], v[234:235] op_sel_hi:[1,0]
	v_pk_mul_f32 v[22:23], v[22:23], v[234:235] op_sel_hi:[1,0]
	v_pk_mul_f32 v[24:25], v[152:153], v[24:25]
	v_pk_mul_f32 v[26:27], v[154:155], v[26:27]
	v_pk_mul_f32 v[20:21], v[156:157], v[20:21]
	v_pk_mul_f32 v[22:23], v[158:159], v[22:23]
	global_store_dwordx4 v200, v[24:27], s[66:67] offset:512
	global_store_dwordx4 v200, v[20:23], s[66:67] offset:528
	v_pk_mul_f32 v[16:17], v[16:17], v[238:239] op_sel_hi:[1,0]
	v_pk_mul_f32 v[18:19], v[18:19], v[238:239] op_sel_hi:[1,0]
	v_pk_mul_f32 v[12:13], v[12:13], v[238:239] op_sel_hi:[1,0]
	v_pk_mul_f32 v[14:15], v[14:15], v[238:239] op_sel_hi:[1,0]
	v_pk_mul_f32 v[16:17], v[144:145], v[16:17]
	v_pk_mul_f32 v[18:19], v[146:147], v[18:19]
	v_pk_mul_f32 v[12:13], v[148:149], v[12:13]
	v_pk_mul_f32 v[14:15], v[150:151], v[14:15]
	global_store_dwordx4 v201, v[16:19], s[66:67]
	global_store_dwordx4 v201, v[12:15], s[66:67] offset:16
	v_pk_mul_f32 v[8:9], v[8:9], v[238:239] op_sel_hi:[1,0]
	v_pk_mul_f32 v[10:11], v[10:11], v[238:239] op_sel_hi:[1,0]
	v_pk_mul_f32 v[4:5], v[4:5], v[238:239] op_sel_hi:[1,0]
	v_pk_mul_f32 v[6:7], v[6:7], v[238:239] op_sel_hi:[1,0]
	v_pk_mul_f32 v[8:9], v[152:153], v[8:9]
	v_pk_mul_f32 v[10:11], v[154:155], v[10:11]
	v_pk_mul_f32 v[4:5], v[156:157], v[4:5]
	v_pk_mul_f32 v[6:7], v[158:159], v[6:7]
	global_store_dwordx4 v201, v[8:11], s[66:67] offset:512
	global_store_dwordx4 v201, v[4:7], s[66:67] offset:528
	s_branch .LBB0_1375

; __device__ __forceinline__ void rmsnorm_rows(const float* x, const float* gain, bf16_t* o, int nrows, int gw, int ngw, int lane) {
;     f32x4 gv[4];
; #pragma unroll
;     for (int j = 0; j < 4; ++j) gv[j] = ldg<f32x4>((const f32x4*)gain + lane + 64 * j);
;     __device__ __forceinline__ void emit(int row, int pn, int col0, float* v) const {
;     ...
;             const size_t o = ((size_t)grp * TG + row) * D + col0;
;             const f32x4 a0 = ldg<f32x4>(xi + o), a1 = ldg<f32x4>(xi + o + 4);
;             f32x4 r0, r1; r0.x = a0.x + v[0]; r0.y = a0.y + v[1]; r0.z = a0.z + v[2]; r0.w = a0.w + v[3]; r1.x = a1.x + v[4]; r1.y = a1.y + v[5]; r1.z = a1.z + v[6]; r1.w = a1.w + v[7];
;             stg<f32x4>(xo + o, r0); stg<f32x4>(xo + o + 4, r1);
.Lwo_na:
	v_mov_b32_e32 v0, 0x25918
	ds_read_b64 v[140:141], v0
	v_lshlrev_b32_e32 v0, 2, v203
	v_readlane_b32 s101, v255, 12
	s_waitcnt lgkmcnt(0)
	s_cmpk_gt_u32 s101, 24
	v_readfirstlane_b32 s100, v140
	v_readfirstlane_b32 s101, v141
	s_cbranch_scc0 .Lwo_l0
	s_add_u32 s100, s100, 0x1000
	s_addc_u32 s101, s101, 0
.Lwo_l0:
	s_nop 4
	global_load_dwordx4 v[144:147], v0, s[100:101]
	global_load_dwordx4 v[148:151], v0, s[100:101] offset:16
	global_load_dwordx4 v[152:155], v0, s[100:101] offset:512
	global_load_dwordx4 v[156:159], v0, s[100:101] offset:528
	global_store_dwordx4 v182, v[128:131], s[66:67]
	global_store_dwordx4 v182, v[124:127], s[66:67] offset:16
	global_store_dwordx4 v182, v[120:123], s[66:67] offset:512
	global_store_dwordx4 v182, v[116:119], s[66:67] offset:528
	global_store_dwordx4 v183, v[112:115], s[66:67]
	global_store_dwordx4 v183, v[108:111], s[66:67] offset:16
	global_store_dwordx4 v183, v[104:107], s[66:67] offset:512
	global_store_dwordx4 v183, v[100:103], s[66:67] offset:528
	global_store_dwordx4 v184, v[96:99], s[66:67]
	global_store_dwordx4 v184, v[92:95], s[66:67] offset:16
	global_store_dwordx4 v184, v[88:91], s[66:67] offset:512
	global_store_dwordx4 v184, v[84:87], s[66:67] offset:528
	global_store_dwordx4 v185, v[80:83], s[66:67]
	global_store_dwordx4 v185, v[76:79], s[66:67] offset:16
	global_store_dwordx4 v185, v[72:75], s[66:67] offset:512
	global_store_dwordx4 v185, v[68:71], s[66:67] offset:528
	global_store_dwordx4 v190, v[64:67], s[66:67]
	global_store_dwordx4 v190, v[60:63], s[66:67] offset:16
	global_store_dwordx4 v190, v[56:59], s[66:67] offset:512
	global_store_dwordx4 v190, v[52:55], s[66:67] offset:528
	global_store_dwordx4 v191, v[48:51], s[66:67]
	global_store_dwordx4 v191, v[44:47], s[66:67] offset:16
	global_store_dwordx4 v191, v[40:43], s[66:67] offset:512
	global_store_dwordx4 v191, v[36:39], s[66:67] offset:528
	global_store_dwordx4 v200, v[32:35], s[66:67]
	global_store_dwordx4 v200, v[28:31], s[66:67] offset:16
	global_store_dwordx4 v200, v[24:27], s[66:67] offset:512
	global_store_dwordx4 v200, v[20:23], s[66:67] offset:528
	global_store_dwordx4 v201, v[16:19], s[66:67]
	global_store_dwordx4 v201, v[12:15], s[66:67] offset:16
	global_store_dwordx4 v201, v[8:11], s[66:67] offset:512
	global_store_dwordx4 v201, v[4:7], s[66:67] offset:528
	v_readfirstlane_b32 s100, v192
	s_cmp_lg_u32 s100, 0
	s_cbranch_scc1 .Lwo_bw
	s_mov_b32 s101, 0

; __device__ __forceinline__ unsigned cvt_pk_bf16(float lo, float hi) { const f32x2 v = {lo, hi}; const bf16x2_native b = __builtin_convertvector(v, bf16x2_native); return __builtin_bit_cast(unsigned, b); }
; __device__ __forceinline__ void rmsnorm_rows(const float* x, const float* gain, bf16_t* o, int nrows, int gw, int ngw, int lane) {
;     ...
;         const float ra = rsqrtf(sa * (1.f / D) + 1e-6f), rbb = rsqrtf(sb * (1.f / D) + 1e-6f);
;         u32x2* oa = (u32x2*)(o + (size_t)r * D) + lane; u32x2* ob = (u32x2*)(o + (size_t)rb * D) + lane;
; #pragma unroll
;         for (int j = 0; j < 4; ++j) { u32x2 w; w.x = cvt_pk_bf16(va[j].x * ra * gv[j].x, va[j].y * ra * gv[j].y); w.y = cvt_pk_bf16(va[j].z * ra * gv[j].z, va[j].w * ra * gv[j].w); stg<u32x2>(oa + 64 * j, w); }
.Lwo_bw:
	s_barrier
	v_lshlrev_b32_e32 v136, 2, v202
	v_add_u32_e32 v137, 0x10000, v136
	v_add_u32_e32 v138, 0x20000, v136
	v_add_u32_e32 v139, 0x30000, v136
	global_load_dword v210, v136, s[98:99] sc1
	global_load_dword v211, v137, s[98:99] sc1
	global_load_dword v212, v138, s[98:99] sc1
	global_load_dword v213, v139, s[98:99] sc1
	global_load_dword v214, v136, s[98:99] offset:64 sc1
	global_load_dword v215, v137, s[98:99] offset:64 sc1
	global_load_dword v216, v138, s[98:99] offset:64 sc1
	global_load_dword v217, v139, s[98:99] offset:64 sc1
	global_load_dword v218, v136, s[98:99] offset:128 sc1
	global_load_dword v219, v137, s[98:99] offset:128 sc1
	global_load_dword v220, v138, s[98:99] offset:128 sc1
	global_load_dword v221, v139, s[98:99] offset:128 sc1
	global_load_dword v222, v136, s[98:99] offset:192 sc1
	global_load_dword v223, v137, s[98:99] offset:192 sc1
	global_load_dword v224, v138, s[98:99] offset:192 sc1
	global_load_dword v225, v139, s[98:99] offset:192 sc1
	global_load_dword v226, v136, s[98:99] offset:512 sc1
	global_load_dword v227, v137, s[98:99] offset:512 sc1
	global_load_dword v228, v138, s[98:99] offset:512 sc1
	global_load_dword v229, v139, s[98:99] offset:512 sc1
	global_load_dword v230, v136, s[98:99] offset:576 sc1
	global_load_dword v231, v137, s[98:99] offset:576 sc1
	global_load_dword v232, v138, s[98:99] offset:576 sc1
	global_load_dword v233, v139, s[98:99] offset:576 sc1
	global_load_dword v234, v136, s[98:99] offset:640 sc1
	global_load_dword v235, v137, s[98:99] offset:640 sc1
	global_load_dword v236, v138, s[98:99] offset:640 sc1
	global_load_dword v237, v139, s[98:99] offset:640 sc1
	global_load_dword v238, v136, s[98:99] offset:704 sc1
	global_load_dword v239, v137, s[98:99] offset:704 sc1
	global_load_dword v240, v138, s[98:99] offset:704 sc1
	global_load_dword v241, v139, s[98:99] offset:704 sc1
	v_mov_b32_e32 v142, 0x358637bd
	v_readfirstlane_b32 s98, v132
	v_readfirstlane_b32 s99, v133
	s_add_u32 s98, s98, 0x2d00000
	s_addc_u32 s99, s99, 0
	v_lshl_add_u32 v143, v202, 10, v203
	v_lshlrev_b32_e32 v143, 1, v143
	v_mov_b32_e32 v132, v143
	v_add_u32_e32 v133, 0x8000, v143
	v_add_u32_e32 v134, 0x10000, v143
	v_add_u32_e32 v135, 0x18000, v143
	v_add_u32_e32 v136, 0x40000, v143
	v_add_u32_e32 v137, 0x48000, v143
	v_add_u32_e32 v138, 0x50000, v143
	v_add_u32_e32 v139, 0x58000, v143
	s_waitcnt vmcnt(0)
	v_add_f32_e32 v210, v210, v211
	v_add_f32_e32 v210, v210, v212
	v_add_f32_e32 v210, v210, v213
	v_fmamk_f32 v210, v210, 0x3a800000, v142
	v_add_f32_e32 v214, v214, v215
	v_add_f32_e32 v214, v214, v216
	v_add_f32_e32 v214, v214, v217
	v_fmamk_f32 v214, v214, 0x3a800000, v142
	v_add_f32_e32 v218, v218, v219
	v_add_f32_e32 v218, v218, v220
	v_add_f32_e32 v218, v218, v221
	v_fmamk_f32 v218, v218, 0x3a800000, v142
	v_add_f32_e32 v222, v222, v223
	v_add_f32_e32 v222, v222, v224
	v_add_f32_e32 v222, v222, v225
	v_fmamk_f32 v222, v222, 0x3a800000, v142
	v_add_f32_e32 v226, v226, v227
	v_add_f32_e32 v226, v226, v228
	v_add_f32_e32 v226, v226, v229
	v_fmamk_f32 v226, v226, 0x3a800000, v142
	v_add_f32_e32 v230, v230, v231
	v_add_f32_e32 v230, v230, v232
	v_add_f32_e32 v230, v230, v233
	v_fmamk_f32 v230, v230, 0x3a800000, v142
	v_add_f32_e32 v234, v234, v235
	v_add_f32_e32 v234, v234, v236
	v_add_f32_e32 v234, v234, v237
	v_fmamk_f32 v234, v234, 0x3a800000, v142
	v_add_f32_e32 v238, v238, v239
	v_add_f32_e32 v238, v238, v240
	v_add_f32_e32 v238, v238, v241
	v_fmamk_f32 v238, v238, 0x3a800000, v142
	v_rsq_f32_e32 v210, v210
	v_rsq_f32_e32 v214, v214
	v_rsq_f32_e32 v218, v218
	v_rsq_f32_e32 v222, v222
	v_rsq_f32_e32 v226, v226
	v_rsq_f32_e32 v230, v230
	v_rsq_f32_e32 v234, v234
	v_rsq_f32_e32 v238, v238
	s_nop 0
	v_pk_mul_f32 v[212:213], v[128:129], v[210:211] op_sel_hi:[1,0]
	v_pk_mul_f32 v[216:217], v[130:131], v[210:211] op_sel_hi:[1,0]
	v_pk_mul_f32 v[220:221], v[124:125], v[210:211] op_sel_hi:[1,0]
	v_pk_mul_f32 v[224:225], v[126:127], v[210:211] op_sel_hi:[1,0]
	v_pk_mul_f32 v[212:213], v[144:145], v[212:213]
	v_pk_mul_f32 v[216:217], v[146:147], v[216:217]
	v_pk_mul_f32 v[220:221], v[148:149], v[220:221]
	v_pk_mul_f32 v[224:225], v[150:151], v[224:225]
	v_cvt_pk_bf16_f32 v160, v212, v213
	v_cvt_pk_bf16_f32 v161, v216, v217
	v_cvt_pk_bf16_f32 v162, v220, v221
	v_cvt_pk_bf16_f32 v163, v224, v225
	global_store_dwordx4 v132, v[160:163], s[98:99]
	v_pk_mul_f32 v[228:229], v[120:121], v[210:211] op_sel_hi:[1,0]
	v_pk_mul_f32 v[232:233], v[122:123], v[210:211] op_sel_hi:[1,0]
	v_pk_mul_f32 v[236:237], v[116:117], v[210:211] op_sel_hi:[1,0]
	v_pk_mul_f32 v[240:241], v[118:119], v[210:211] op_sel_hi:[1,0]
	v_pk_mul_f32 v[228:229], v[152:153], v[228:229]
	v_pk_mul_f32 v[232:233], v[154:155], v[232:233]
	v_pk_mul_f32 v[236:237], v[156:157], v[236:237]
	v_pk_mul_f32 v[240:241], v[158:159], v[240:241]
	v_cvt_pk_bf16_f32 v160, v228, v229
	v_cvt_pk_bf16_f32 v161, v232, v233
	v_cvt_pk_bf16_f32 v162, v236, v237
	v_cvt_pk_bf16_f32 v163, v240, v241
	global_store_dwordx4 v132, v[160:163], s[98:99] offset:256
	v_pk_mul_f32 v[212:213], v[112:113], v[214:215] op_sel_hi:[1,0]
	v_pk_mul_f32 v[216:217], v[114:115], v[214:215] op_sel_hi:[1,0]
	v_pk_mul_f32 v[220:221], v[108:109], v[214:215] op_sel_hi:[1,0]
	v_pk_mul_f32 v[224:225], v[110:111], v[214:215] op_sel_hi:[1,0]
	v_pk_mul_f32 v[212:213], v[144:145], v[212:213]
	v_pk_mul_f32 v[216:217], v[146:147], v[216:217]
	v_pk_mul_f32 v[220:221], v[148:149], v[220:221]
	v_pk_mul_f32 v[224:225], v[150:151], v[224:225]
	v_cvt_pk_bf16_f32 v160, v212, v213
	v_cvt_pk_bf16_f32 v161, v216, v217
	v_cvt_pk_bf16_f32 v162, v220, v221
	v_cvt_pk_bf16_f32 v163, v224, v225
	global_store_dwordx4 v133, v[160:163], s[98:99]
; __device__ __forceinline__ unsigned cvt_pk_bf16(float lo, float hi) { const f32x2 v = {lo, hi}; const bf16x2_native b = __builtin_convertvector(v, bf16x2_native); return __builtin_bit_cast(unsigned, b); }
; __device__ __forceinline__ void rmsnorm_rows(const float* x, const float* gain, bf16_t* o, int nrows, int gw, int ngw, int lane) {
;     ...
;         u32x2* oa = (u32x2*)(o + (size_t)r * D) + lane; u32x2* ob = (u32x2*)(o + (size_t)rb * D) + lane;
; #pragma unroll
;         for (int j = 0; j < 4; ++j) { u32x2 w; w.x = cvt_pk_bf16(va[j].x * ra * gv[j].x, va[j].y * ra * gv[j].y); w.y = cvt_pk_bf16(va[j].z * ra * gv[j].z, va[j].w * ra * gv[j].w); stg<u32x2>(oa + 64 * j, w); }
;         if (has2) {
; #pragma unroll
;             for (int j = 0; j < 4; ++j) { u32x2 w; w.x = cvt_pk_bf16(vb[j].x * rbb * gv[j].x, vb[j].y * rbb * gv[j].y); w.y = cvt_pk_bf16(vb[j].z * rbb * gv[j].z, vb[j].w * rbb * gv[j].w); stg<u32x2>(ob + 64 * j, w); } }
	v_pk_mul_f32 v[228:229], v[104:105], v[214:215] op_sel_hi:[1,0]
	v_pk_mul_f32 v[232:233], v[106:107], v[214:215] op_sel_hi:[1,0]
	v_pk_mul_f32 v[236:237], v[100:101], v[214:215] op_sel_hi:[1,0]
	v_pk_mul_f32 v[240:241], v[102:103], v[214:215] op_sel_hi:[1,0]
	v_pk_mul_f32 v[228:229], v[152:153], v[228:229]
	v_pk_mul_f32 v[232:233], v[154:155], v[232:233]
	v_pk_mul_f32 v[236:237], v[156:157], v[236:237]
	v_pk_mul_f32 v[240:241], v[158:159], v[240:241]
	v_cvt_pk_bf16_f32 v160, v228, v229
	v_cvt_pk_bf16_f32 v161, v232, v233
	v_cvt_pk_bf16_f32 v162, v236, v237
	v_cvt_pk_bf16_f32 v163, v240, v241
	global_store_dwordx4 v133, v[160:163], s[98:99] offset:256
	v_pk_mul_f32 v[212:213], v[96:97], v[218:219] op_sel_hi:[1,0]
	v_pk_mul_f32 v[216:217], v[98:99], v[218:219] op_sel_hi:[1,0]
	v_pk_mul_f32 v[220:221], v[92:93], v[218:219] op_sel_hi:[1,0]
	v_pk_mul_f32 v[224:225], v[94:95], v[218:219] op_sel_hi:[1,0]
	v_pk_mul_f32 v[212:213], v[144:145], v[212:213]
	v_pk_mul_f32 v[216:217], v[146:147], v[216:217]
	v_pk_mul_f32 v[220:221], v[148:149], v[220:221]
	v_pk_mul_f32 v[224:225], v[150:151], v[224:225]
	v_cvt_pk_bf16_f32 v160, v212, v213
	v_cvt_pk_bf16_f32 v161, v216, v217
	v_cvt_pk_bf16_f32 v162, v220, v221
	v_cvt_pk_bf16_f32 v163, v224, v225
	global_store_dwordx4 v134, v[160:163], s[98:99]
	v_pk_mul_f32 v[228:229], v[88:89], v[218:219] op_sel_hi:[1,0]
	v_pk_mul_f32 v[232:233], v[90:91], v[218:219] op_sel_hi:[1,0]
	v_pk_mul_f32 v[236:237], v[84:85], v[218:219] op_sel_hi:[1,0]
	v_pk_mul_f32 v[240:241], v[86:87], v[218:219] op_sel_hi:[1,0]
	v_pk_mul_f32 v[228:229], v[152:153], v[228:229]
	v_pk_mul_f32 v[232:233], v[154:155], v[232:233]
	v_pk_mul_f32 v[236:237], v[156:157], v[236:237]
	v_pk_mul_f32 v[240:241], v[158:159], v[240:241]
	v_cvt_pk_bf16_f32 v160, v228, v229
	v_cvt_pk_bf16_f32 v161, v232, v233
	v_cvt_pk_bf16_f32 v162, v236, v237
	v_cvt_pk_bf16_f32 v163, v240, v241
	global_store_dwordx4 v134, v[160:163], s[98:99] offset:256
	v_pk_mul_f32 v[212:213], v[80:81], v[222:223] op_sel_hi:[1,0]
	v_pk_mul_f32 v[216:217], v[82:83], v[222:223] op_sel_hi:[1,0]
	v_pk_mul_f32 v[220:221], v[76:77], v[222:223] op_sel_hi:[1,0]
	v_pk_mul_f32 v[224:225], v[78:79], v[222:223] op_sel_hi:[1,0]
	v_pk_mul_f32 v[212:213], v[144:145], v[212:213]
	v_pk_mul_f32 v[216:217], v[146:147], v[216:217]
	v_pk_mul_f32 v[220:221], v[148:149], v[220:221]
	v_pk_mul_f32 v[224:225], v[150:151], v[224:225]
	v_cvt_pk_bf16_f32 v160, v212, v213
	v_cvt_pk_bf16_f32 v161, v216, v217
	v_cvt_pk_bf16_f32 v162, v220, v221
	v_cvt_pk_bf16_f32 v163, v224, v225
	global_store_dwordx4 v135, v[160:163], s[98:99]
	v_pk_mul_f32 v[228:229], v[72:73], v[222:223] op_sel_hi:[1,0]
	v_pk_mul_f32 v[232:233], v[74:75], v[222:223] op_sel_hi:[1,0]
	v_pk_mul_f32 v[236:237], v[68:69], v[222:223] op_sel_hi:[1,0]
	v_pk_mul_f32 v[240:241], v[70:71], v[222:223] op_sel_hi:[1,0]
	v_pk_mul_f32 v[228:229], v[152:153], v[228:229]
	v_pk_mul_f32 v[232:233], v[154:155], v[232:233]
	v_pk_mul_f32 v[236:237], v[156:157], v[236:237]
	v_pk_mul_f32 v[240:241], v[158:159], v[240:241]
	v_cvt_pk_bf16_f32 v160, v228, v229
	v_cvt_pk_bf16_f32 v161, v232, v233
	v_cvt_pk_bf16_f32 v162, v236, v237
	v_cvt_pk_bf16_f32 v163, v240, v241
	global_store_dwordx4 v135, v[160:163], s[98:99] offset:256
	v_pk_mul_f32 v[212:213], v[64:65], v[226:227] op_sel_hi:[1,0]
	v_pk_mul_f32 v[216:217], v[66:67], v[226:227] op_sel_hi:[1,0]
	v_pk_mul_f32 v[220:221], v[60:61], v[226:227] op_sel_hi:[1,0]
	v_pk_mul_f32 v[224:225], v[62:63], v[226:227] op_sel_hi:[1,0]
	v_pk_mul_f32 v[212:213], v[144:145], v[212:213]
	v_pk_mul_f32 v[216:217], v[146:147], v[216:217]
	v_pk_mul_f32 v[220:221], v[148:149], v[220:221]
	v_pk_mul_f32 v[224:225], v[150:151], v[224:225]
	v_cvt_pk_bf16_f32 v160, v212, v213
	v_cvt_pk_bf16_f32 v161, v216, v217
	v_cvt_pk_bf16_f32 v162, v220, v221
	v_cvt_pk_bf16_f32 v163, v224, v225
	global_store_dwordx4 v136, v[160:163], s[98:99]
	v_pk_mul_f32 v[228:229], v[56:57], v[226:227] op_sel_hi:[1,0]
	v_pk_mul_f32 v[232:233], v[58:59], v[226:227] op_sel_hi:[1,0]
	v_pk_mul_f32 v[236:237], v[52:53], v[226:227] op_sel_hi:[1,0]
	v_pk_mul_f32 v[240:241], v[54:55], v[226:227] op_sel_hi:[1,0]
	v_pk_mul_f32 v[228:229], v[152:153], v[228:229]
	v_pk_mul_f32 v[232:233], v[154:155], v[232:233]
; __device__ __forceinline__ unsigned cvt_pk_bf16(float lo, float hi) { const f32x2 v = {lo, hi}; const bf16x2_native b = __builtin_convertvector(v, bf16x2_native); return __builtin_bit_cast(unsigned, b); }
; __device__ __forceinline__ void rmsnorm_rows(const float* x, const float* gain, bf16_t* o, int nrows, int gw, int ngw, int lane) {
;     ...
;         u32x2* oa = (u32x2*)(o + (size_t)r * D) + lane; u32x2* ob = (u32x2*)(o + (size_t)rb * D) + lane;
; #pragma unroll
;         for (int j = 0; j < 4; ++j) { u32x2 w; w.x = cvt_pk_bf16(va[j].x * ra * gv[j].x, va[j].y * ra * gv[j].y); w.y = cvt_pk_bf16(va[j].z * ra * gv[j].z, va[j].w * ra * gv[j].w); stg<u32x2>(oa + 64 * j, w); }
;         if (has2) {
; #pragma unroll
;             for (int j = 0; j < 4; ++j) { u32x2 w; w.x = cvt_pk_bf16(vb[j].x * rbb * gv[j].x, vb[j].y * rbb * gv[j].y); w.y = cvt_pk_bf16(vb[j].z * rbb * gv[j].z, vb[j].w * rbb * gv[j].w); stg<u32x2>(ob + 64 * j, w); } }
	v_pk_mul_f32 v[236:237], v[156:157], v[236:237]
	v_pk_mul_f32 v[240:241], v[158:159], v[240:241]
	v_cvt_pk_bf16_f32 v160, v228, v229
	v_cvt_pk_bf16_f32 v161, v232, v233
	v_cvt_pk_bf16_f32 v162, v236, v237
	v_cvt_pk_bf16_f32 v163, v240, v241
	global_store_dwordx4 v136, v[160:163], s[98:99] offset:256
	v_pk_mul_f32 v[212:213], v[48:49], v[230:231] op_sel_hi:[1,0]
	v_pk_mul_f32 v[216:217], v[50:51], v[230:231] op_sel_hi:[1,0]
	v_pk_mul_f32 v[220:221], v[44:45], v[230:231] op_sel_hi:[1,0]
	v_pk_mul_f32 v[224:225], v[46:47], v[230:231] op_sel_hi:[1,0]
	v_pk_mul_f32 v[212:213], v[144:145], v[212:213]
	v_pk_mul_f32 v[216:217], v[146:147], v[216:217]
	v_pk_mul_f32 v[220:221], v[148:149], v[220:221]
	v_pk_mul_f32 v[224:225], v[150:151], v[224:225]
	v_cvt_pk_bf16_f32 v160, v212, v213
	v_cvt_pk_bf16_f32 v161, v216, v217
	v_cvt_pk_bf16_f32 v162, v220, v221
	v_cvt_pk_bf16_f32 v163, v224, v225
	global_store_dwordx4 v137, v[160:163], s[98:99]
	v_pk_mul_f32 v[228:229], v[40:41], v[230:231] op_sel_hi:[1,0]
	v_pk_mul_f32 v[232:233], v[42:43], v[230:231] op_sel_hi:[1,0]
	v_pk_mul_f32 v[236:237], v[36:37], v[230:231] op_sel_hi:[1,0]
	v_pk_mul_f32 v[240:241], v[38:39], v[230:231] op_sel_hi:[1,0]
	v_pk_mul_f32 v[228:229], v[152:153], v[228:229]
	v_pk_mul_f32 v[232:233], v[154:155], v[232:233]
	v_pk_mul_f32 v[236:237], v[156:157], v[236:237]
	v_pk_mul_f32 v[240:241], v[158:159], v[240:241]
	v_cvt_pk_bf16_f32 v160, v228, v229
	v_cvt_pk_bf16_f32 v161, v232, v233
	v_cvt_pk_bf16_f32 v162, v236, v237
	v_cvt_pk_bf16_f32 v163, v240, v241
	global_store_dwordx4 v137, v[160:163], s[98:99] offset:256
	v_pk_mul_f32 v[212:213], v[32:33], v[234:235] op_sel_hi:[1,0]
	v_pk_mul_f32 v[216:217], v[34:35], v[234:235] op_sel_hi:[1,0]
	v_pk_mul_f32 v[220:221], v[28:29], v[234:235] op_sel_hi:[1,0]
	v_pk_mul_f32 v[224:225], v[30:31], v[234:235] op_sel_hi:[1,0]
	v_pk_mul_f32 v[212:213], v[144:145], v[212:213]
	v_pk_mul_f32 v[216:217], v[146:147], v[216:217]
	v_pk_mul_f32 v[220:221], v[148:149], v[220:221]
	v_pk_mul_f32 v[224:225], v[150:151], v[224:225]
	v_cvt_pk_bf16_f32 v160, v212, v213
	v_cvt_pk_bf16_f32 v161, v216, v217
	v_cvt_pk_bf16_f32 v162, v220, v221
	v_cvt_pk_bf16_f32 v163, v224, v225
	global_store_dwordx4 v138, v[160:163], s[98:99]
	v_pk_mul_f32 v[228:229], v[24:25], v[234:235] op_sel_hi:[1,0]
	v_pk_mul_f32 v[232:233], v[26:27], v[234:235] op_sel_hi:[1,0]
	v_pk_mul_f32 v[236:237], v[20:21], v[234:235] op_sel_hi:[1,0]
	v_pk_mul_f32 v[240:241], v[22:23], v[234:235] op_sel_hi:[1,0]
	v_pk_mul_f32 v[228:229], v[152:153], v[228:229]
	v_pk_mul_f32 v[232:233], v[154:155], v[232:233]
	v_pk_mul_f32 v[236:237], v[156:157], v[236:237]
	v_pk_mul_f32 v[240:241], v[158:159], v[240:241]
	v_cvt_pk_bf16_f32 v160, v228, v229
	v_cvt_pk_bf16_f32 v161, v232, v233
	v_cvt_pk_bf16_f32 v162, v236, v237
	v_cvt_pk_bf16_f32 v163, v240, v241
	global_store_dwordx4 v138, v[160:163], s[98:99] offset:256
	v_pk_mul_f32 v[212:213], v[16:17], v[238:239] op_sel_hi:[1,0]
	v_pk_mul_f32 v[216:217], v[18:19], v[238:239] op_sel_hi:[1,0]
	v_pk_mul_f32 v[220:221], v[12:13], v[238:239] op_sel_hi:[1,0]
	v_pk_mul_f32 v[224:225], v[14:15], v[238:239] op_sel_hi:[1,0]
	v_pk_mul_f32 v[212:213], v[144:145], v[212:213]
	v_pk_mul_f32 v[216:217], v[146:147], v[216:217]
	v_pk_mul_f32 v[220:221], v[148:149], v[220:221]
	v_pk_mul_f32 v[224:225], v[150:151], v[224:225]
	v_cvt_pk_bf16_f32 v160, v212, v213
	v_cvt_pk_bf16_f32 v161, v216, v217
	v_cvt_pk_bf16_f32 v162, v220, v221
	v_cvt_pk_bf16_f32 v163, v224, v225
	global_store_dwordx4 v139, v[160:163], s[98:99]
	v_pk_mul_f32 v[228:229], v[8:9], v[238:239] op_sel_hi:[1,0]
	v_pk_mul_f32 v[232:233], v[10:11], v[238:239] op_sel_hi:[1,0]
	v_pk_mul_f32 v[236:237], v[4:5], v[238:239] op_sel_hi:[1,0]
	v_pk_mul_f32 v[240:241], v[6:7], v[238:239] op_sel_hi:[1,0]
	v_pk_mul_f32 v[228:229], v[152:153], v[228:229]
	v_pk_mul_f32 v[232:233], v[154:155], v[232:233]
	v_pk_mul_f32 v[236:237], v[156:157], v[236:237]
	v_pk_mul_f32 v[240:241], v[158:159], v[240:241]
	v_cvt_pk_bf16_f32 v160, v228, v229
	v_cvt_pk_bf16_f32 v161, v232, v233
	v_cvt_pk_bf16_f32 v162, v236, v237
	v_cvt_pk_bf16_f32 v163, v240, v241
	global_store_dwordx4 v139, v[160:163], s[98:99] offset:256
	s_branch .LBB0_1375
